# w_in_transpose_single_batch
# speedup vs baseline: 1.0049x; 1.0049x over previous
; #define LAS __attribute__((address_space(3)))
; __device__ __forceinline__ void p0_transpose_item(const float* W, int N, int ksrc0, int nsrc0, const float* ksc, bf16_t* WT, int nrow0, int kdst0, LAS float* scr, int lane) {
; #pragma unroll 8
;     for (int i = 0; i < 32; ++i) { const int kk = 2 * i + (lane >> 5); float v = W[(size_t)(ksrc0 + kk) * N + nsrc0 + (lane & 31)]; if (ksc) v *= ksc[ksrc0 + kk]; scr[kk * 33 + (lane & 31)] = v; }
;     asm volatile("s_waitcnt lgkmcnt(0)" ::: "memory");
.Lwt_fast:
	v_lshl_add_u64 v[60:61], v[40:41], 0, s[16:17]
	global_load_dword v70, v[60:61], off
	v_lshl_add_u64 v[60:61], v[36:37], 0, s[16:17]
	global_load_dword v71, v[60:61], off
	v_lshl_add_u64 v[60:61], v[34:35], 0, s[16:17]
	global_load_dword v72, v[60:61], off
	v_lshl_add_u64 v[60:61], v[32:33], 0, s[16:17]
	global_load_dword v73, v[60:61], off
	v_lshl_add_u64 v[60:61], v[30:31], 0, s[16:17]
	global_load_dword v74, v[60:61], off
	v_lshl_add_u64 v[60:61], v[28:29], 0, s[16:17]
	global_load_dword v75, v[60:61], off
	v_lshl_add_u64 v[60:61], v[26:27], 0, s[16:17]
	global_load_dword v76, v[60:61], off
	v_lshl_add_u64 v[60:61], v[22:23], 0, s[16:17]
	global_load_dword v77, v[60:61], off
	v_lshl_add_u64 v[62:63], s[18:19], 0, v[38:39]
	global_load_dword v102, v[62:63], off
	v_lshl_add_u64 v[64:65], s[18:19], 0, v[24:25]
	global_load_dword v103, v[64:65], off offset:8
	global_load_dword v104, v[64:65], off offset:16
	global_load_dword v105, v[64:65], off offset:24
	global_load_dword v106, v[64:65], off offset:32
	global_load_dword v107, v[64:65], off offset:40
	global_load_dword v108, v[64:65], off offset:48
	global_load_dword v109, v[64:65], off offset:56
	s_add_u32 s16, s16, 0x54000
	s_addc_u32 s17, s17, 0
	s_add_u32 s18, s18, 64
	s_addc_u32 s19, s19, 0
	v_lshl_add_u64 v[60:61], v[40:41], 0, s[16:17]
	global_load_dword v78, v[60:61], off
	v_lshl_add_u64 v[60:61], v[36:37], 0, s[16:17]
	global_load_dword v79, v[60:61], off
	v_lshl_add_u64 v[60:61], v[34:35], 0, s[16:17]
	global_load_dword v80, v[60:61], off
	v_lshl_add_u64 v[60:61], v[32:33], 0, s[16:17]
	global_load_dword v81, v[60:61], off
	v_lshl_add_u64 v[60:61], v[30:31], 0, s[16:17]
	global_load_dword v82, v[60:61], off
	v_lshl_add_u64 v[60:61], v[28:29], 0, s[16:17]
	global_load_dword v83, v[60:61], off
	v_lshl_add_u64 v[60:61], v[26:27], 0, s[16:17]
	global_load_dword v84, v[60:61], off
	v_lshl_add_u64 v[60:61], v[22:23], 0, s[16:17]
	global_load_dword v85, v[60:61], off
	v_lshl_add_u64 v[62:63], s[18:19], 0, v[38:39]
	global_load_dword v110, v[62:63], off
	v_lshl_add_u64 v[64:65], s[18:19], 0, v[24:25]
	global_load_dword v111, v[64:65], off offset:8
	global_load_dword v112, v[64:65], off offset:16
	global_load_dword v113, v[64:65], off offset:24
	global_load_dword v114, v[64:65], off offset:32
	global_load_dword v115, v[64:65], off offset:40
	global_load_dword v116, v[64:65], off offset:48
	global_load_dword v117, v[64:65], off offset:56
	s_add_u32 s16, s16, 0x54000
	s_addc_u32 s17, s17, 0
	s_add_u32 s18, s18, 64
	s_addc_u32 s19, s19, 0
	v_lshl_add_u64 v[60:61], v[40:41], 0, s[16:17]
	global_load_dword v86, v[60:61], off
	v_lshl_add_u64 v[60:61], v[36:37], 0, s[16:17]
	global_load_dword v87, v[60:61], off
	v_lshl_add_u64 v[60:61], v[34:35], 0, s[16:17]
	global_load_dword v88, v[60:61], off
	v_lshl_add_u64 v[60:61], v[32:33], 0, s[16:17]
	global_load_dword v89, v[60:61], off
	v_lshl_add_u64 v[60:61], v[30:31], 0, s[16:17]
	global_load_dword v90, v[60:61], off
	v_lshl_add_u64 v[60:61], v[28:29], 0, s[16:17]
	global_load_dword v91, v[60:61], off
	v_lshl_add_u64 v[60:61], v[26:27], 0, s[16:17]
	global_load_dword v92, v[60:61], off
	v_lshl_add_u64 v[60:61], v[22:23], 0, s[16:17]
	global_load_dword v93, v[60:61], off
	v_lshl_add_u64 v[62:63], s[18:19], 0, v[38:39]
	global_load_dword v118, v[62:63], off
	v_lshl_add_u64 v[64:65], s[18:19], 0, v[24:25]
	global_load_dword v119, v[64:65], off offset:8
	global_load_dword v120, v[64:65], off offset:16
	global_load_dword v121, v[64:65], off offset:24
	global_load_dword v122, v[64:65], off offset:32
	global_load_dword v123, v[64:65], off offset:40
	global_load_dword v124, v[64:65], off offset:48
	global_load_dword v125, v[64:65], off offset:56
	s_add_u32 s16, s16, 0x54000
	s_addc_u32 s17, s17, 0
	s_add_u32 s18, s18, 64
	s_addc_u32 s19, s19, 0
	v_lshl_add_u64 v[60:61], v[40:41], 0, s[16:17]
	global_load_dword v94, v[60:61], off
	v_lshl_add_u64 v[60:61], v[36:37], 0, s[16:17]
	global_load_dword v95, v[60:61], off
	v_lshl_add_u64 v[60:61], v[34:35], 0, s[16:17]
	global_load_dword v96, v[60:61], off
	v_lshl_add_u64 v[60:61], v[32:33], 0, s[16:17]
	global_load_dword v97, v[60:61], off
	v_lshl_add_u64 v[60:61], v[30:31], 0, s[16:17]
	global_load_dword v98, v[60:61], off
	v_lshl_add_u64 v[60:61], v[28:29], 0, s[16:17]
	global_load_dword v99, v[60:61], off
	v_lshl_add_u64 v[60:61], v[26:27], 0, s[16:17]
	global_load_dword v100, v[60:61], off
	v_lshl_add_u64 v[60:61], v[22:23], 0, s[16:17]
	global_load_dword v101, v[60:61], off
	v_lshl_add_u64 v[62:63], s[18:19], 0, v[38:39]
	global_load_dword v126, v[62:63], off
	v_lshl_add_u64 v[64:65], s[18:19], 0, v[24:25]
	global_load_dword v127, v[64:65], off offset:8
	global_load_dword v128, v[64:65], off offset:16
	global_load_dword v129, v[64:65], off offset:24
	global_load_dword v130, v[64:65], off offset:32
	global_load_dword v131, v[64:65], off offset:40
	global_load_dword v132, v[64:65], off offset:48
	global_load_dword v133, v[64:65], off offset:56
	s_waitcnt vmcnt(0)
; #define LAS __attribute__((address_space(3)))
; __device__ __forceinline__ void p0_transpose_item(const float* W, int N, int ksrc0, int nsrc0, const float* ksc, bf16_t* WT, int nrow0, int kdst0, LAS float* scr, int lane) {
; #pragma unroll 8
;     for (int i = 0; i < 32; ++i) { const int kk = 2 * i + (lane >> 5); float v = W[(size_t)(ksrc0 + kk) * N + nsrc0 + (lane & 31)]; if (ksc) v *= ksc[ksrc0 + kk]; scr[kk * 33 + (lane & 31)] = v; }
;     asm volatile("s_waitcnt lgkmcnt(0)" ::: "memory");
	v_mul_f32_e32 v70, v70, v102
	v_mul_f32_e32 v71, v71, v103
	v_mul_f32_e32 v72, v72, v104
	v_mul_f32_e32 v73, v73, v105
	v_mul_f32_e32 v74, v74, v106
	v_mul_f32_e32 v75, v75, v107
	v_mul_f32_e32 v76, v76, v108
	v_mul_f32_e32 v77, v77, v109
	v_mul_f32_e32 v78, v78, v110
	v_mul_f32_e32 v79, v79, v111
	v_mul_f32_e32 v80, v80, v112
	v_mul_f32_e32 v81, v81, v113
	v_mul_f32_e32 v82, v82, v114
	v_mul_f32_e32 v83, v83, v115
	v_mul_f32_e32 v84, v84, v116
	v_mul_f32_e32 v85, v85, v117
	v_mul_f32_e32 v86, v86, v118
	v_mul_f32_e32 v87, v87, v119
	v_mul_f32_e32 v88, v88, v120
	v_mul_f32_e32 v89, v89, v121
	v_mul_f32_e32 v90, v90, v122
	v_mul_f32_e32 v91, v91, v123
	v_mul_f32_e32 v92, v92, v124
	v_mul_f32_e32 v93, v93, v125
	v_mul_f32_e32 v94, v94, v126
	v_mul_f32_e32 v95, v95, v127
	v_mul_f32_e32 v96, v96, v128
	v_mul_f32_e32 v97, v97, v129
	v_mul_f32_e32 v98, v98, v130
	v_mul_f32_e32 v99, v99, v131
	v_mul_f32_e32 v100, v100, v132
	v_mul_f32_e32 v101, v101, v133
	ds_write_b32 v2, v70
	ds_write_b32 v2, v71 offset:264
	ds_write_b32 v2, v72 offset:528
	ds_write_b32 v2, v73 offset:792
	ds_write_b32 v2, v74 offset:1056
	ds_write_b32 v2, v75 offset:1320
	ds_write_b32 v2, v76 offset:1584
	ds_write_b32 v2, v77 offset:1848
	ds_write_b32 v2, v78 offset:2112
	ds_write_b32 v2, v79 offset:2376
	ds_write_b32 v2, v80 offset:2640
	ds_write_b32 v2, v81 offset:2904
	ds_write_b32 v2, v82 offset:3168
	ds_write_b32 v2, v83 offset:3432
	ds_write_b32 v2, v84 offset:3696
	ds_write_b32 v2, v85 offset:3960
	ds_write_b32 v2, v86 offset:4224
	ds_write_b32 v2, v87 offset:4488
	ds_write_b32 v2, v88 offset:4752
	ds_write_b32 v2, v89 offset:5016
	ds_write_b32 v2, v90 offset:5280
	ds_write_b32 v2, v91 offset:5544
	ds_write_b32 v2, v92 offset:5808
	ds_write_b32 v2, v93 offset:6072
	ds_write_b32 v2, v94 offset:6336
	ds_write_b32 v2, v95 offset:6600
	ds_write_b32 v2, v96 offset:6864
	ds_write_b32 v2, v97 offset:7128
	ds_write_b32 v2, v98 offset:7392
	ds_write_b32 v2, v99 offset:7656
	ds_write_b32 v2, v100 offset:7920
	ds_write_b32 v2, v101 offset:8184
	s_branch .LBB0_44
